# final rmsnorm loop and P0 rmsnorm-rows loop rewritten: scalar control, norm weights hoisted, all row loads issued at once, next row prefetched
# speedup vs baseline: 1.0445x; 1.0044x over previous
; __device__ __forceinline__ unsigned pk2(float lo, float hi) { unsigned r; asm("v_cvt_pk_bf16_f32 %0, %1, %2" : "=v"(r) : "v"(lo), "v"(hi)); return r; }
; __device__ __forceinline__ const float* row_src(const Params& p, int r) {
;     if (r < ROWS_P) { const int b = r / TP, t = r - b * TP;
;         if (t < PADR) return nullptr;
;         if (t < 128) return p.meta + (size_t)(t - PADR) * DM;
;         return p.x_prompt + ((size_t)b * 2048 + (t - 128)) * DM; }
;     return p.x_sample + (size_t)(r - ROWS_P) * DM;
; }
; __device__ __forceinline__ void phase_prep(const Params& p, float* tile) {
;     ...
;     for (int r = blockIdx.x * 8 + wid; r < TROWS; r += gridDim.x * 8) {
;         const float* src = row_src(p, r); bf16_t* dst = XN + (size_t)r * DM;
;         if (!src) {
; #pragma unroll
;             for (int i = 0; i < 4; ++i) *(u32x4*)(dst + (lane + 64 * i) * 8) = (u32x4){0u, 0u, 0u, 0u};
;         } else {
;             f32x4 v[8]; float ss = 0.f;
; #pragma unroll
;             for (int i = 0; i < 8; ++i) { v[i] = __builtin_nontemporal_load((const f32x4*)src + lane + 64 * i); ss += v[i][0] * v[i][0] + v[i][1] * v[i][1] + v[i][2] * v[i][2] + v[i][3] * v[i][3]; }
; #pragma unroll
;             for (int o = 32; o >= 1; o >>= 1) ss += __shfl_xor(ss, o);
;             const float rs = rsqrtf(ss * (1.0f / DM) + EPS);
; #pragma unroll
;             for (int i = 0; i < 8; ++i) { const f32x4 w = ((const f32x4*)p.norm_w)[lane + 64 * i];
;                 u32x2 o; o.x = pk2(v[i][0] * rs * w[0], v[i][1] * rs * w[1]); o.y = pk2(v[i][2] * rs * w[2], v[i][3] * rs * w[3]);
;                 *(u32x2*)(dst + (lane + 64 * i) * 4) = o; }
;         }
.LBB0_19:
	s_or_b64 exec, exec, s[0:1]
	v_mov_b32_e32 v37, v192
	s_lshl_b32 s17, s83, 3
	v_ashrrev_i32_e32 v58, 6, v37
	v_add_u32_e32 v20, s17, v58
	s_movk_i32 s0, 0x2600
	v_and_b32_e32 v36, 63, v37
	v_cmp_gt_i32_e32 vcc, s0, v20
	v_mbcnt_lo_u32_b32 v184, -1, 0
	s_and_saveexec_b64 s[0:1], vcc
	s_cbranch_execz .LBB0_36
	v_readfirstlane_b32 s36, v20
	v_readlane_b32 s38, v244, 12
	v_readlane_b32 s39, v244, 13
	v_readlane_b32 s40, v244, 14
	v_readlane_b32 s41, v244, 15
	v_readlane_b32 s42, v244, 22
	v_readlane_b32 s43, v244, 23
	v_readlane_b32 s44, v244, 24
	v_readlane_b32 s45, v244, 25
	v_lshlrev_b32_e32 v96, 4, v36
	v_lshlrev_b32_e32 v105, 3, v36
	v_mov_b32_e32 v97, 0
	v_lshlrev_b32_e32 v107, 2, v36
	v_mov_b32_e32 v99, 0
	v_add_u32_e32 v98, 0x1000, v96
	v_mov_b32_e32 v38, 0x358637bd
	s_mov_b32 s51, 0x800000
	global_load_dwordx4 v[64:67], v96, s[44:45] offset:0
	global_load_dwordx4 v[68:71], v96, s[44:45] offset:1024
	global_load_dwordx4 v[72:75], v96, s[44:45] offset:2048
	global_load_dwordx4 v[76:79], v96, s[44:45] offset:3072
	global_load_dwordx4 v[80:83], v98, s[44:45] offset:0
	global_load_dwordx4 v[84:87], v98, s[44:45] offset:1024
	global_load_dwordx4 v[88:91], v98, s[44:45] offset:2048
	global_load_dwordx4 v[92:95], v98, s[44:45] offset:3072
	s_mov_b32 s55, 0
	s_cmp_lt_u32 s36, 0x2600
	s_cbranch_scc0 .Lp0_inv_a0
	s_cmp_gt_u32 s36, 0x21ff
	s_cbranch_scc1 .Lp0_smp_a0
	s_mul_hi_u32 s52, s36, 0x78787879
	s_lshr_b32 s52, s52, 10
	s_mul_i32 s53, s52, 0x880
	s_sub_u32 s53, s36, s53
	s_cmp_lt_u32 s53, 0x70
	s_cbranch_scc1 .Lp0_inv_a0
	s_cmp_lt_u32 s53, 0x80
	s_cbranch_scc1 .Lp0_meta_a0
	s_lshl_b32 s52, s52, 24
	s_sub_u32 s53, s53, 0x80
	s_lshl_b32 s53, s53, 13
	s_add_u32 s52, s52, s53
	s_add_u32 s48, s38, s52
	s_addc_u32 s49, s39, 0
	s_branch .Lp0_srcdone_a0
.Lp0_meta_a0:
	s_sub_u32 s53, s53, 0x70
	s_lshl_b32 s53, s53, 13
	s_add_u32 s48, s42, s53
	s_addc_u32 s49, s43, 0
	s_branch .Lp0_srcdone_a0
.Lp0_smp_a0:
	s_sub_u32 s53, s36, 0x2200
	s_lshl_b32 s53, s53, 13
	s_add_u32 s48, s40, s53
	s_addc_u32 s49, s41, 0
	s_branch .Lp0_srcdone_a0
.Lp0_inv_a0:
	s_mov_b32 s55, 1
	s_mov_b32 s48, s40
	s_mov_b32 s49, s41
.Lp0_srcdone_a0:
	global_load_dwordx4 v[0:3], v96, s[48:49] offset:0 nt
	global_load_dwordx4 v[4:7], v96, s[48:49] offset:1024 nt
	global_load_dwordx4 v[8:11], v96, s[48:49] offset:2048 nt
	global_load_dwordx4 v[12:15], v96, s[48:49] offset:3072 nt
	global_load_dwordx4 v[16:19], v98, s[48:49] offset:0 nt
	global_load_dwordx4 v[20:23], v98, s[48:49] offset:1024 nt
	global_load_dwordx4 v[24:27], v98, s[48:49] offset:2048 nt
	global_load_dwordx4 v[28:31], v98, s[48:49] offset:3072 nt
	s_add_u32 s37, s36, 0x800
	s_mov_b32 s58, 0
	s_cmp_lt_u32 s37, 0x2600
	s_cbranch_scc0 .Lp0_inv_b0
	s_cmp_gt_u32 s37, 0x21ff
	s_cbranch_scc1 .Lp0_smp_b0
	s_mul_hi_u32 s52, s37, 0x78787879
	s_lshr_b32 s52, s52, 10
	s_mul_i32 s53, s52, 0x880
	s_sub_u32 s53, s37, s53
	s_cmp_lt_u32 s53, 0x70
	s_cbranch_scc1 .Lp0_inv_b0
	s_cmp_lt_u32 s53, 0x80
	s_cbranch_scc1 .Lp0_meta_b0
	s_lshl_b32 s52, s52, 24
	s_sub_u32 s53, s53, 0x80
	s_lshl_b32 s53, s53, 13
	s_add_u32 s52, s52, s53
	s_add_u32 s56, s38, s52
	s_addc_u32 s57, s39, 0
	s_branch .Lp0_srcdone_b0
.Lp0_meta_b0:
	s_sub_u32 s53, s53, 0x70
	s_lshl_b32 s53, s53, 13
	s_add_u32 s56, s42, s53
	s_addc_u32 s57, s43, 0
	s_branch .Lp0_srcdone_b0
.Lp0_smp_b0:
	s_sub_u32 s53, s37, 0x2200
	s_lshl_b32 s53, s53, 13
	s_add_u32 s56, s40, s53
	s_addc_u32 s57, s41, 0
	s_branch .Lp0_srcdone_b0
.Lp0_inv_b0:
	s_mov_b32 s58, 1
	s_mov_b32 s56, s40
	s_mov_b32 s57, s41
; __device__ __forceinline__ unsigned pk2(float lo, float hi) { unsigned r; asm("v_cvt_pk_bf16_f32 %0, %1, %2" : "=v"(r) : "v"(lo), "v"(hi)); return r; }
; __device__ __forceinline__ void phase_prep(const Params& p, float* tile) {
;     ...
;     for (int r = blockIdx.x * 8 + wid; r < TROWS; r += gridDim.x * 8) {
;         const float* src = row_src(p, r); bf16_t* dst = XN + (size_t)r * DM;
;         if (!src) {
; #pragma unroll
;             for (int i = 0; i < 4; ++i) *(u32x4*)(dst + (lane + 64 * i) * 8) = (u32x4){0u, 0u, 0u, 0u};
;         } else {
;             f32x4 v[8]; float ss = 0.f;
; #pragma unroll
;             for (int i = 0; i < 8; ++i) { v[i] = __builtin_nontemporal_load((const f32x4*)src + lane + 64 * i); ss += v[i][0] * v[i][0] + v[i][1] * v[i][1] + v[i][2] * v[i][2] + v[i][3] * v[i][3]; }
; #pragma unroll
;             for (int o = 32; o >= 1; o >>= 1) ss += __shfl_xor(ss, o);
;             const float rs = rsqrtf(ss * (1.0f / DM) + EPS);
; #pragma unroll
;             for (int i = 0; i < 8; ++i) { const f32x4 w = ((const f32x4*)p.norm_w)[lane + 64 * i];
;                 u32x2 o; o.x = pk2(v[i][0] * rs * w[0], v[i][1] * rs * w[1]); o.y = pk2(v[i][2] * rs * w[2], v[i][3] * rs * w[3]);
;                 *(u32x2*)(dst + (lane + 64 * i) * 4) = o; }
;         }
.Lp0_srcdone_b0:
	global_load_dwordx4 v[120:123], v96, s[56:57] offset:0 nt
	global_load_dwordx4 v[124:127], v96, s[56:57] offset:1024 nt
	global_load_dwordx4 v[128:131], v96, s[56:57] offset:2048 nt
	global_load_dwordx4 v[132:135], v96, s[56:57] offset:3072 nt
	global_load_dwordx4 v[136:139], v98, s[56:57] offset:0 nt
	global_load_dwordx4 v[140:143], v98, s[56:57] offset:1024 nt
	global_load_dwordx4 v[144:147], v98, s[56:57] offset:2048 nt
	global_load_dwordx4 v[148:151], v98, s[56:57] offset:3072 nt
	s_lshl_b32 s54, s36, 12
	s_add_u32 s46, s88, s54
	s_addc_u32 s47, s89, 0
	s_cmp_lg_u32 s55, 0
	s_cbranch_scc1 .Lp0_zero_pa0
	s_waitcnt vmcnt(8)
	v_mul_f32_e32 v32, v0, v0
	v_mul_f32_e32 v33, v1, v1
	v_mul_f32_e32 v34, v2, v2
	v_mul_f32_e32 v35, v3, v3
	v_fmac_f32_e32 v32, v4, v4
	v_fmac_f32_e32 v33, v5, v5
	v_fmac_f32_e32 v34, v6, v6
	v_fmac_f32_e32 v35, v7, v7
	v_fmac_f32_e32 v32, v8, v8
	v_fmac_f32_e32 v33, v9, v9
	v_fmac_f32_e32 v34, v10, v10
	v_fmac_f32_e32 v35, v11, v11
	v_fmac_f32_e32 v32, v12, v12
	v_fmac_f32_e32 v33, v13, v13
	v_fmac_f32_e32 v34, v14, v14
	v_fmac_f32_e32 v35, v15, v15
	v_fmac_f32_e32 v32, v16, v16
	v_fmac_f32_e32 v33, v17, v17
	v_fmac_f32_e32 v34, v18, v18
	v_fmac_f32_e32 v35, v19, v19
	v_fmac_f32_e32 v32, v20, v20
	v_fmac_f32_e32 v33, v21, v21
	v_fmac_f32_e32 v34, v22, v22
	v_fmac_f32_e32 v35, v23, v23
	v_fmac_f32_e32 v32, v24, v24
	v_fmac_f32_e32 v33, v25, v25
	v_fmac_f32_e32 v34, v26, v26
	v_fmac_f32_e32 v35, v27, v27
	v_fmac_f32_e32 v32, v28, v28
	v_fmac_f32_e32 v33, v29, v29
	v_fmac_f32_e32 v34, v30, v30
	v_fmac_f32_e32 v35, v31, v31
	v_add_f32_e32 v32, v32, v33
	v_add_f32_e32 v34, v34, v35
	s_nop 0
	v_add_f32_e32 v32, v32, v34
	v_xor_b32_e32 v33, 0x80, v107
	ds_bpermute_b32 v34, v33, v32
	s_waitcnt lgkmcnt(0)
	v_add_f32_e32 v32, v32, v34
	v_xor_b32_e32 v33, 0x40, v107
	ds_bpermute_b32 v34, v33, v32
	s_waitcnt lgkmcnt(0)
	v_add_f32_e32 v32, v32, v34
	v_xor_b32_e32 v33, 0x20, v107
	ds_bpermute_b32 v34, v33, v32
	s_waitcnt lgkmcnt(0)
	v_add_f32_e32 v32, v32, v34
	v_xor_b32_e32 v33, 0x10, v107
	ds_bpermute_b32 v34, v33, v32
	s_waitcnt lgkmcnt(0)
	v_add_f32_e32 v32, v32, v34
	v_xor_b32_e32 v33, 0x8, v107
	ds_bpermute_b32 v34, v33, v32
	s_waitcnt lgkmcnt(0)
	v_add_f32_e32 v32, v32, v34
	v_xor_b32_e32 v33, 0x4, v107
	ds_bpermute_b32 v34, v33, v32
	s_waitcnt lgkmcnt(0)
	v_add_f32_e32 v32, v32, v34
	v_fmamk_f32 v32, v32, 0x3a000000, v38
	v_mul_f32_e32 v33, 0x4b800000, v32
	v_cmp_gt_f32_e32 vcc, s51, v32
	s_nop 1
	v_cndmask_b32_e32 v32, v32, v33, vcc
	v_rsq_f32_e32 v32, v32
	s_nop 0
	v_mul_f32_e32 v33, 0x45800000, v32
	v_cndmask_b32_e32 v32, v32, v33, vcc
	v_mul_f32_e32 v40, v0, v32
	v_mul_f32_e32 v41, v1, v32
	v_mul_f32_e32 v42, v2, v32
	v_mul_f32_e32 v43, v3, v32
	v_mul_f32_e32 v40, v64, v40
	v_mul_f32_e32 v41, v65, v41
	v_mul_f32_e32 v42, v66, v42
	v_mul_f32_e32 v43, v67, v43
	v_cvt_pk_bf16_f32 v48, v40, v41
	v_cvt_pk_bf16_f32 v49, v42, v43
	global_store_dwordx2 v105, v[48:49], s[46:47] offset:0
	v_mul_f32_e32 v44, v4, v32
	v_mul_f32_e32 v45, v5, v32
	v_mul_f32_e32 v46, v6, v32
	v_mul_f32_e32 v47, v7, v32
	v_mul_f32_e32 v44, v68, v44
	v_mul_f32_e32 v45, v69, v45
	v_mul_f32_e32 v46, v70, v46
	v_mul_f32_e32 v47, v71, v47
	v_cvt_pk_bf16_f32 v50, v44, v45
	v_cvt_pk_bf16_f32 v51, v46, v47
	global_store_dwordx2 v105, v[50:51], s[46:47] offset:512
	v_mul_f32_e32 v40, v8, v32
	v_mul_f32_e32 v41, v9, v32
	v_mul_f32_e32 v42, v10, v32
	v_mul_f32_e32 v43, v11, v32
	v_mul_f32_e32 v40, v72, v40
	v_mul_f32_e32 v41, v73, v41
	v_mul_f32_e32 v42, v74, v42
	v_mul_f32_e32 v43, v75, v43
	v_cvt_pk_bf16_f32 v52, v40, v41
	v_cvt_pk_bf16_f32 v53, v42, v43
	global_store_dwordx2 v105, v[52:53], s[46:47] offset:1024
	v_mul_f32_e32 v44, v12, v32
	v_mul_f32_e32 v45, v13, v32
	v_mul_f32_e32 v46, v14, v32
	v_mul_f32_e32 v47, v15, v32
	v_mul_f32_e32 v44, v76, v44
	v_mul_f32_e32 v45, v77, v45
	v_mul_f32_e32 v46, v78, v46
	v_mul_f32_e32 v47, v79, v47
	v_cvt_pk_bf16_f32 v54, v44, v45
	v_cvt_pk_bf16_f32 v55, v46, v47
	global_store_dwordx2 v105, v[54:55], s[46:47] offset:1536
	v_mul_f32_e32 v40, v16, v32
	v_mul_f32_e32 v41, v17, v32
	v_mul_f32_e32 v42, v18, v32
	v_mul_f32_e32 v43, v19, v32
	v_mul_f32_e32 v40, v80, v40
	v_mul_f32_e32 v41, v81, v41
	v_mul_f32_e32 v42, v82, v42
	v_mul_f32_e32 v43, v83, v43
	v_cvt_pk_bf16_f32 v48, v40, v41
	v_cvt_pk_bf16_f32 v49, v42, v43
	global_store_dwordx2 v105, v[48:49], s[46:47] offset:2048
	v_mul_f32_e32 v44, v20, v32
	v_mul_f32_e32 v45, v21, v32
	v_mul_f32_e32 v46, v22, v32
	v_mul_f32_e32 v47, v23, v32
	v_mul_f32_e32 v44, v84, v44
	v_mul_f32_e32 v45, v85, v45
	v_mul_f32_e32 v46, v86, v46
	v_mul_f32_e32 v47, v87, v47
	v_cvt_pk_bf16_f32 v50, v44, v45
	v_cvt_pk_bf16_f32 v51, v46, v47
	global_store_dwordx2 v105, v[50:51], s[46:47] offset:2560
	v_mul_f32_e32 v40, v24, v32
	v_mul_f32_e32 v41, v25, v32
	v_mul_f32_e32 v42, v26, v32
	v_mul_f32_e32 v43, v27, v32
	v_mul_f32_e32 v40, v88, v40
	v_mul_f32_e32 v41, v89, v41
	v_mul_f32_e32 v42, v90, v42
	v_mul_f32_e32 v43, v91, v43
	v_cvt_pk_bf16_f32 v52, v40, v41
	v_cvt_pk_bf16_f32 v53, v42, v43
	global_store_dwordx2 v105, v[52:53], s[46:47] offset:3072
	v_mul_f32_e32 v44, v28, v32
	v_mul_f32_e32 v45, v29, v32
	v_mul_f32_e32 v46, v30, v32
	v_mul_f32_e32 v47, v31, v32
	v_mul_f32_e32 v44, v92, v44
	v_mul_f32_e32 v45, v93, v45
	v_mul_f32_e32 v46, v94, v46
	v_mul_f32_e32 v47, v95, v47
	v_cvt_pk_bf16_f32 v54, v44, v45
	v_cvt_pk_bf16_f32 v55, v46, v47
	global_store_dwordx2 v105, v[54:55], s[46:47] offset:3584
	s_branch .Lp0_done_pa0
.Lp0_zero_pa0:
	v_mov_b32_e32 v56, 0
	v_mov_b32_e32 v57, 0
	global_store_dwordx2 v105, v[56:57], s[46:47] offset:0
	global_store_dwordx2 v105, v[56:57], s[46:47] offset:512
	global_store_dwordx2 v105, v[56:57], s[46:47] offset:1024
	global_store_dwordx2 v105, v[56:57], s[46:47] offset:1536
	global_store_dwordx2 v105, v[56:57], s[46:47] offset:2048
	global_store_dwordx2 v105, v[56:57], s[46:47] offset:2560
	global_store_dwordx2 v105, v[56:57], s[46:47] offset:3072
	global_store_dwordx2 v105, v[56:57], s[46:47] offset:3584
.Lp0_done_pa0:
.Lp0_loop:
	s_cmp_lt_u32 s37, 0x2600
	s_cbranch_scc0 .Lp0_exit
	s_add_u32 s36, s37, 0x800
	s_mov_b32 s55, 0
	s_cmp_lt_u32 s36, 0x2600
	s_cbranch_scc0 .Lp0_inv_a1
	s_cmp_gt_u32 s36, 0x21ff
	s_cbranch_scc1 .Lp0_smp_a1
	s_mul_hi_u32 s52, s36, 0x78787879
	s_lshr_b32 s52, s52, 10
	s_mul_i32 s53, s52, 0x880
	s_sub_u32 s53, s36, s53
	s_cmp_lt_u32 s53, 0x70
	s_cbranch_scc1 .Lp0_inv_a1
	s_cmp_lt_u32 s53, 0x80
	s_cbranch_scc1 .Lp0_meta_a1
	s_lshl_b32 s52, s52, 24
	s_sub_u32 s53, s53, 0x80
	s_lshl_b32 s53, s53, 13
	s_add_u32 s52, s52, s53
	s_add_u32 s48, s38, s52
	s_addc_u32 s49, s39, 0
	s_branch .Lp0_srcdone_a1

; __device__ __forceinline__ unsigned pk2(float lo, float hi) { unsigned r; asm("v_cvt_pk_bf16_f32 %0, %1, %2" : "=v"(r) : "v"(lo), "v"(hi)); return r; }
; __device__ __forceinline__ void phase_prep(const Params& p, float* tile) {
;     ...
;     for (int r = blockIdx.x * 8 + wid; r < TROWS; r += gridDim.x * 8) {
;         const float* src = row_src(p, r); bf16_t* dst = XN + (size_t)r * DM;
;         if (!src) {
; #pragma unroll
;             for (int i = 0; i < 4; ++i) *(u32x4*)(dst + (lane + 64 * i) * 8) = (u32x4){0u, 0u, 0u, 0u};
;         } else {
;             f32x4 v[8]; float ss = 0.f;
; #pragma unroll
;             for (int i = 0; i < 8; ++i) { v[i] = __builtin_nontemporal_load((const f32x4*)src + lane + 64 * i); ss += v[i][0] * v[i][0] + v[i][1] * v[i][1] + v[i][2] * v[i][2] + v[i][3] * v[i][3]; }
; #pragma unroll
;             for (int o = 32; o >= 1; o >>= 1) ss += __shfl_xor(ss, o);
;             const float rs = rsqrtf(ss * (1.0f / DM) + EPS);
; #pragma unroll
;             for (int i = 0; i < 8; ++i) { const f32x4 w = ((const f32x4*)p.norm_w)[lane + 64 * i];
;                 u32x2 o; o.x = pk2(v[i][0] * rs * w[0], v[i][1] * rs * w[1]); o.y = pk2(v[i][2] * rs * w[2], v[i][3] * rs * w[3]);
;                 *(u32x2*)(dst + (lane + 64 * i) * 4) = o; }
;         }
.Lp0_srcdone_a1:
	global_load_dwordx4 v[0:3], v96, s[48:49] offset:0 nt
	global_load_dwordx4 v[4:7], v96, s[48:49] offset:1024 nt
	global_load_dwordx4 v[8:11], v96, s[48:49] offset:2048 nt
	global_load_dwordx4 v[12:15], v96, s[48:49] offset:3072 nt
	global_load_dwordx4 v[16:19], v98, s[48:49] offset:0 nt
	global_load_dwordx4 v[20:23], v98, s[48:49] offset:1024 nt
	global_load_dwordx4 v[24:27], v98, s[48:49] offset:2048 nt
	global_load_dwordx4 v[28:31], v98, s[48:49] offset:3072 nt
	s_lshl_b32 s54, s37, 12
	s_add_u32 s46, s88, s54
	s_addc_u32 s47, s89, 0
	s_cmp_lg_u32 s58, 0
	s_cbranch_scc1 .Lp0_zero_pb
	s_waitcnt vmcnt(16)
	v_mul_f32_e32 v32, v120, v120
	v_mul_f32_e32 v33, v121, v121
	v_mul_f32_e32 v34, v122, v122
	v_mul_f32_e32 v35, v123, v123
	v_fmac_f32_e32 v32, v124, v124
	v_fmac_f32_e32 v33, v125, v125
	v_fmac_f32_e32 v34, v126, v126
	v_fmac_f32_e32 v35, v127, v127
	v_fmac_f32_e32 v32, v128, v128
	v_fmac_f32_e32 v33, v129, v129
	v_fmac_f32_e32 v34, v130, v130
	v_fmac_f32_e32 v35, v131, v131
	v_fmac_f32_e32 v32, v132, v132
	v_fmac_f32_e32 v33, v133, v133
	v_fmac_f32_e32 v34, v134, v134
	v_fmac_f32_e32 v35, v135, v135
	v_fmac_f32_e32 v32, v136, v136
	v_fmac_f32_e32 v33, v137, v137
	v_fmac_f32_e32 v34, v138, v138
	v_fmac_f32_e32 v35, v139, v139
	v_fmac_f32_e32 v32, v140, v140
	v_fmac_f32_e32 v33, v141, v141
	v_fmac_f32_e32 v34, v142, v142
	v_fmac_f32_e32 v35, v143, v143
	v_fmac_f32_e32 v32, v144, v144
	v_fmac_f32_e32 v33, v145, v145
	v_fmac_f32_e32 v34, v146, v146
	v_fmac_f32_e32 v35, v147, v147
	v_fmac_f32_e32 v32, v148, v148
	v_fmac_f32_e32 v33, v149, v149
	v_fmac_f32_e32 v34, v150, v150
	v_fmac_f32_e32 v35, v151, v151
	v_add_f32_e32 v32, v32, v33
	v_add_f32_e32 v34, v34, v35
	s_nop 0
	v_add_f32_e32 v32, v32, v34
	v_xor_b32_e32 v33, 0x80, v107
	ds_bpermute_b32 v34, v33, v32
	s_waitcnt lgkmcnt(0)
	v_add_f32_e32 v32, v32, v34
	v_xor_b32_e32 v33, 0x40, v107
	ds_bpermute_b32 v34, v33, v32
	s_waitcnt lgkmcnt(0)
	v_add_f32_e32 v32, v32, v34
	v_xor_b32_e32 v33, 0x20, v107
	ds_bpermute_b32 v34, v33, v32
	s_waitcnt lgkmcnt(0)
	v_add_f32_e32 v32, v32, v34
	v_xor_b32_e32 v33, 0x10, v107
	ds_bpermute_b32 v34, v33, v32
	s_waitcnt lgkmcnt(0)
	v_add_f32_e32 v32, v32, v34
	v_xor_b32_e32 v33, 0x8, v107
	ds_bpermute_b32 v34, v33, v32
	s_waitcnt lgkmcnt(0)
	v_add_f32_e32 v32, v32, v34
	v_xor_b32_e32 v33, 0x4, v107
	ds_bpermute_b32 v34, v33, v32
	s_waitcnt lgkmcnt(0)
	v_add_f32_e32 v32, v32, v34
	v_fmamk_f32 v32, v32, 0x3a000000, v38
	v_mul_f32_e32 v33, 0x4b800000, v32
	v_cmp_gt_f32_e32 vcc, s51, v32
	s_nop 1
	v_cndmask_b32_e32 v32, v32, v33, vcc
	v_rsq_f32_e32 v32, v32
	s_nop 0
	v_mul_f32_e32 v33, 0x45800000, v32
	v_cndmask_b32_e32 v32, v32, v33, vcc
	v_mul_f32_e32 v40, v120, v32
	v_mul_f32_e32 v41, v121, v32
	v_mul_f32_e32 v42, v122, v32
	v_mul_f32_e32 v43, v123, v32
	v_mul_f32_e32 v40, v64, v40
	v_mul_f32_e32 v41, v65, v41
	v_mul_f32_e32 v42, v66, v42
	v_mul_f32_e32 v43, v67, v43
	v_cvt_pk_bf16_f32 v48, v40, v41
	v_cvt_pk_bf16_f32 v49, v42, v43
	global_store_dwordx2 v105, v[48:49], s[46:47] offset:0
	v_mul_f32_e32 v44, v124, v32
	v_mul_f32_e32 v45, v125, v32
	v_mul_f32_e32 v46, v126, v32
	v_mul_f32_e32 v47, v127, v32
	v_mul_f32_e32 v44, v68, v44
	v_mul_f32_e32 v45, v69, v45
	v_mul_f32_e32 v46, v70, v46
	v_mul_f32_e32 v47, v71, v47
	v_cvt_pk_bf16_f32 v50, v44, v45
	v_cvt_pk_bf16_f32 v51, v46, v47
	global_store_dwordx2 v105, v[50:51], s[46:47] offset:512
	v_mul_f32_e32 v40, v128, v32
	v_mul_f32_e32 v41, v129, v32
	v_mul_f32_e32 v42, v130, v32
	v_mul_f32_e32 v43, v131, v32
	v_mul_f32_e32 v40, v72, v40
	v_mul_f32_e32 v41, v73, v41
	v_mul_f32_e32 v42, v74, v42
	v_mul_f32_e32 v43, v75, v43
	v_cvt_pk_bf16_f32 v52, v40, v41
	v_cvt_pk_bf16_f32 v53, v42, v43
	global_store_dwordx2 v105, v[52:53], s[46:47] offset:1024
	v_mul_f32_e32 v44, v132, v32
	v_mul_f32_e32 v45, v133, v32
	v_mul_f32_e32 v46, v134, v32
	v_mul_f32_e32 v47, v135, v32
	v_mul_f32_e32 v44, v76, v44
	v_mul_f32_e32 v45, v77, v45
	v_mul_f32_e32 v46, v78, v46
	v_mul_f32_e32 v47, v79, v47
	v_cvt_pk_bf16_f32 v54, v44, v45
	v_cvt_pk_bf16_f32 v55, v46, v47
	global_store_dwordx2 v105, v[54:55], s[46:47] offset:1536
	v_mul_f32_e32 v40, v136, v32
	v_mul_f32_e32 v41, v137, v32
	v_mul_f32_e32 v42, v138, v32
	v_mul_f32_e32 v43, v139, v32
	v_mul_f32_e32 v40, v80, v40
	v_mul_f32_e32 v41, v81, v41
	v_mul_f32_e32 v42, v82, v42
	v_mul_f32_e32 v43, v83, v43
	v_cvt_pk_bf16_f32 v48, v40, v41
	v_cvt_pk_bf16_f32 v49, v42, v43
	global_store_dwordx2 v105, v[48:49], s[46:47] offset:2048
	v_mul_f32_e32 v44, v140, v32
	v_mul_f32_e32 v45, v141, v32
	v_mul_f32_e32 v46, v142, v32
	v_mul_f32_e32 v47, v143, v32
	v_mul_f32_e32 v44, v84, v44
	v_mul_f32_e32 v45, v85, v45
	v_mul_f32_e32 v46, v86, v46
	v_mul_f32_e32 v47, v87, v47
	v_cvt_pk_bf16_f32 v50, v44, v45
	v_cvt_pk_bf16_f32 v51, v46, v47
	global_store_dwordx2 v105, v[50:51], s[46:47] offset:2560
	v_mul_f32_e32 v40, v144, v32
	v_mul_f32_e32 v41, v145, v32
	v_mul_f32_e32 v42, v146, v32
	v_mul_f32_e32 v43, v147, v32
	v_mul_f32_e32 v40, v88, v40
	v_mul_f32_e32 v41, v89, v41
	v_mul_f32_e32 v42, v90, v42
	v_mul_f32_e32 v43, v91, v43
	v_cvt_pk_bf16_f32 v52, v40, v41
	v_cvt_pk_bf16_f32 v53, v42, v43
	global_store_dwordx2 v105, v[52:53], s[46:47] offset:3072
	v_mul_f32_e32 v44, v148, v32
	v_mul_f32_e32 v45, v149, v32
	v_mul_f32_e32 v46, v150, v32
	v_mul_f32_e32 v47, v151, v32
	v_mul_f32_e32 v44, v92, v44
	v_mul_f32_e32 v45, v93, v45
	v_mul_f32_e32 v46, v94, v46
	v_mul_f32_e32 v47, v95, v47
	v_cvt_pk_bf16_f32 v54, v44, v45
	v_cvt_pk_bf16_f32 v55, v46, v47
	global_store_dwordx2 v105, v[54:55], s[46:47] offset:3584
	s_branch .Lp0_done_pb

; __device__ __forceinline__ const float* row_src(const Params& p, int r) {
;     if (r < ROWS_P) { const int b = r / TP, t = r - b * TP;
;         if (t < PADR) return nullptr;
;         if (t < 128) return p.meta + (size_t)(t - PADR) * DM;
;         return p.x_prompt + ((size_t)b * 2048 + (t - 128)) * DM; }
;     return p.x_sample + (size_t)(r - ROWS_P) * DM;
; }
; __device__ __forceinline__ void phase_prep(const Params& p, float* tile) {
;     ...
;     for (int r = blockIdx.x * 8 + wid; r < TROWS; r += gridDim.x * 8) {
;         const float* src = row_src(p, r); bf16_t* dst = XN + (size_t)r * DM;
.Lp0_done_pb:
	s_cmp_lt_u32 s36, 0x2600
	s_cbranch_scc0 .Lp0_exit
	s_add_u32 s37, s36, 0x800
	s_mov_b32 s58, 0
	s_cmp_lt_u32 s37, 0x2600
	s_cbranch_scc0 .Lp0_inv_b1
	s_cmp_gt_u32 s37, 0x21ff
	s_cbranch_scc1 .Lp0_smp_b1
	s_mul_hi_u32 s52, s37, 0x78787879
	s_lshr_b32 s52, s52, 10
	s_mul_i32 s53, s52, 0x880
	s_sub_u32 s53, s37, s53
	s_cmp_lt_u32 s53, 0x70
	s_cbranch_scc1 .Lp0_inv_b1
	s_cmp_lt_u32 s53, 0x80
	s_cbranch_scc1 .Lp0_meta_b1
	s_lshl_b32 s52, s52, 24
	s_sub_u32 s53, s53, 0x80
	s_lshl_b32 s53, s53, 13
	s_add_u32 s52, s52, s53
	s_add_u32 s56, s38, s52
	s_addc_u32 s57, s39, 0
	s_branch .Lp0_srcdone_b1

; __device__ __forceinline__ unsigned pk2(float lo, float hi) { unsigned r; asm("v_cvt_pk_bf16_f32 %0, %1, %2" : "=v"(r) : "v"(lo), "v"(hi)); return r; }
; __device__ __forceinline__ void phase_prep(const Params& p, float* tile) {
;     ...
;             f32x4 v[8]; float ss = 0.f;
; #pragma unroll
;             for (int i = 0; i < 8; ++i) { v[i] = __builtin_nontemporal_load((const f32x4*)src + lane + 64 * i); ss += v[i][0] * v[i][0] + v[i][1] * v[i][1] + v[i][2] * v[i][2] + v[i][3] * v[i][3]; }
; #pragma unroll
;             for (int o = 32; o >= 1; o >>= 1) ss += __shfl_xor(ss, o);
;             const float rs = rsqrtf(ss * (1.0f / DM) + EPS);
; #pragma unroll
;             for (int i = 0; i < 8; ++i) { const f32x4 w = ((const f32x4*)p.norm_w)[lane + 64 * i];
;                 u32x2 o; o.x = pk2(v[i][0] * rs * w[0], v[i][1] * rs * w[1]); o.y = pk2(v[i][2] * rs * w[2], v[i][3] * rs * w[3]);
;                 *(u32x2*)(dst + (lane + 64 * i) * 4) = o; }
;         }
.Lp0_srcdone_b1:
	global_load_dwordx4 v[120:123], v96, s[56:57] offset:0 nt
	global_load_dwordx4 v[124:127], v96, s[56:57] offset:1024 nt
	global_load_dwordx4 v[128:131], v96, s[56:57] offset:2048 nt
	global_load_dwordx4 v[132:135], v96, s[56:57] offset:3072 nt
	global_load_dwordx4 v[136:139], v98, s[56:57] offset:0 nt
	global_load_dwordx4 v[140:143], v98, s[56:57] offset:1024 nt
	global_load_dwordx4 v[144:147], v98, s[56:57] offset:2048 nt
	global_load_dwordx4 v[148:151], v98, s[56:57] offset:3072 nt
	s_lshl_b32 s54, s36, 12
	s_add_u32 s46, s88, s54
	s_addc_u32 s47, s89, 0
	s_cmp_lg_u32 s55, 0
	s_cbranch_scc1 .Lp0_zero_pa
	s_waitcnt vmcnt(16)
	v_mul_f32_e32 v32, v0, v0
	v_mul_f32_e32 v33, v1, v1
	v_mul_f32_e32 v34, v2, v2
	v_mul_f32_e32 v35, v3, v3
	v_fmac_f32_e32 v32, v4, v4
	v_fmac_f32_e32 v33, v5, v5
	v_fmac_f32_e32 v34, v6, v6
	v_fmac_f32_e32 v35, v7, v7
	v_fmac_f32_e32 v32, v8, v8
	v_fmac_f32_e32 v33, v9, v9
	v_fmac_f32_e32 v34, v10, v10
	v_fmac_f32_e32 v35, v11, v11
	v_fmac_f32_e32 v32, v12, v12
	v_fmac_f32_e32 v33, v13, v13
	v_fmac_f32_e32 v34, v14, v14
	v_fmac_f32_e32 v35, v15, v15
	v_fmac_f32_e32 v32, v16, v16
	v_fmac_f32_e32 v33, v17, v17
	v_fmac_f32_e32 v34, v18, v18
	v_fmac_f32_e32 v35, v19, v19
	v_fmac_f32_e32 v32, v20, v20
	v_fmac_f32_e32 v33, v21, v21
	v_fmac_f32_e32 v34, v22, v22
	v_fmac_f32_e32 v35, v23, v23
	v_fmac_f32_e32 v32, v24, v24
	v_fmac_f32_e32 v33, v25, v25
	v_fmac_f32_e32 v34, v26, v26
	v_fmac_f32_e32 v35, v27, v27
	v_fmac_f32_e32 v32, v28, v28
	v_fmac_f32_e32 v33, v29, v29
	v_fmac_f32_e32 v34, v30, v30
	v_fmac_f32_e32 v35, v31, v31
	v_add_f32_e32 v32, v32, v33
	v_add_f32_e32 v34, v34, v35
	s_nop 0
	v_add_f32_e32 v32, v32, v34
	v_xor_b32_e32 v33, 0x80, v107
	ds_bpermute_b32 v34, v33, v32
	s_waitcnt lgkmcnt(0)
	v_add_f32_e32 v32, v32, v34
	v_xor_b32_e32 v33, 0x40, v107
	ds_bpermute_b32 v34, v33, v32
	s_waitcnt lgkmcnt(0)
	v_add_f32_e32 v32, v32, v34
	v_xor_b32_e32 v33, 0x20, v107
	ds_bpermute_b32 v34, v33, v32
	s_waitcnt lgkmcnt(0)
	v_add_f32_e32 v32, v32, v34
	v_xor_b32_e32 v33, 0x10, v107
	ds_bpermute_b32 v34, v33, v32
	s_waitcnt lgkmcnt(0)
	v_add_f32_e32 v32, v32, v34
	v_xor_b32_e32 v33, 0x8, v107
	ds_bpermute_b32 v34, v33, v32
	s_waitcnt lgkmcnt(0)
	v_add_f32_e32 v32, v32, v34
	v_xor_b32_e32 v33, 0x4, v107
	ds_bpermute_b32 v34, v33, v32
	s_waitcnt lgkmcnt(0)
	v_add_f32_e32 v32, v32, v34
	v_fmamk_f32 v32, v32, 0x3a000000, v38
	v_mul_f32_e32 v33, 0x4b800000, v32
	v_cmp_gt_f32_e32 vcc, s51, v32
	s_nop 1
	v_cndmask_b32_e32 v32, v32, v33, vcc
	v_rsq_f32_e32 v32, v32
	s_nop 0
	v_mul_f32_e32 v33, 0x45800000, v32
	v_cndmask_b32_e32 v32, v32, v33, vcc
	v_mul_f32_e32 v40, v0, v32
	v_mul_f32_e32 v41, v1, v32
	v_mul_f32_e32 v42, v2, v32
	v_mul_f32_e32 v43, v3, v32
	v_mul_f32_e32 v40, v64, v40
	v_mul_f32_e32 v41, v65, v41
	v_mul_f32_e32 v42, v66, v42
	v_mul_f32_e32 v43, v67, v43
	v_cvt_pk_bf16_f32 v48, v40, v41
	v_cvt_pk_bf16_f32 v49, v42, v43
	global_store_dwordx2 v105, v[48:49], s[46:47] offset:0
	v_mul_f32_e32 v44, v4, v32
	v_mul_f32_e32 v45, v5, v32
	v_mul_f32_e32 v46, v6, v32
	v_mul_f32_e32 v47, v7, v32
	v_mul_f32_e32 v44, v68, v44
	v_mul_f32_e32 v45, v69, v45
	v_mul_f32_e32 v46, v70, v46
	v_mul_f32_e32 v47, v71, v47
	v_cvt_pk_bf16_f32 v50, v44, v45
	v_cvt_pk_bf16_f32 v51, v46, v47
	global_store_dwordx2 v105, v[50:51], s[46:47] offset:512
	v_mul_f32_e32 v40, v8, v32
	v_mul_f32_e32 v41, v9, v32
	v_mul_f32_e32 v42, v10, v32
	v_mul_f32_e32 v43, v11, v32
	v_mul_f32_e32 v40, v72, v40
	v_mul_f32_e32 v41, v73, v41
	v_mul_f32_e32 v42, v74, v42
	v_mul_f32_e32 v43, v75, v43
	v_cvt_pk_bf16_f32 v52, v40, v41
	v_cvt_pk_bf16_f32 v53, v42, v43
	global_store_dwordx2 v105, v[52:53], s[46:47] offset:1024
	v_mul_f32_e32 v44, v12, v32
	v_mul_f32_e32 v45, v13, v32
	v_mul_f32_e32 v46, v14, v32
	v_mul_f32_e32 v47, v15, v32
	v_mul_f32_e32 v44, v76, v44
	v_mul_f32_e32 v45, v77, v45
	v_mul_f32_e32 v46, v78, v46
	v_mul_f32_e32 v47, v79, v47
	v_cvt_pk_bf16_f32 v54, v44, v45
	v_cvt_pk_bf16_f32 v55, v46, v47
	global_store_dwordx2 v105, v[54:55], s[46:47] offset:1536
	v_mul_f32_e32 v40, v16, v32
	v_mul_f32_e32 v41, v17, v32
	v_mul_f32_e32 v42, v18, v32
	v_mul_f32_e32 v43, v19, v32
	v_mul_f32_e32 v40, v80, v40
	v_mul_f32_e32 v41, v81, v41
	v_mul_f32_e32 v42, v82, v42
	v_mul_f32_e32 v43, v83, v43
	v_cvt_pk_bf16_f32 v48, v40, v41
	v_cvt_pk_bf16_f32 v49, v42, v43
	global_store_dwordx2 v105, v[48:49], s[46:47] offset:2048
	v_mul_f32_e32 v44, v20, v32
	v_mul_f32_e32 v45, v21, v32
	v_mul_f32_e32 v46, v22, v32
	v_mul_f32_e32 v47, v23, v32
	v_mul_f32_e32 v44, v84, v44
	v_mul_f32_e32 v45, v85, v45
	v_mul_f32_e32 v46, v86, v46
	v_mul_f32_e32 v47, v87, v47
	v_cvt_pk_bf16_f32 v50, v44, v45
	v_cvt_pk_bf16_f32 v51, v46, v47
	global_store_dwordx2 v105, v[50:51], s[46:47] offset:2560
	v_mul_f32_e32 v40, v24, v32
	v_mul_f32_e32 v41, v25, v32
	v_mul_f32_e32 v42, v26, v32
	v_mul_f32_e32 v43, v27, v32
	v_mul_f32_e32 v40, v88, v40
	v_mul_f32_e32 v41, v89, v41
	v_mul_f32_e32 v42, v90, v42
	v_mul_f32_e32 v43, v91, v43
	v_cvt_pk_bf16_f32 v52, v40, v41
	v_cvt_pk_bf16_f32 v53, v42, v43
	global_store_dwordx2 v105, v[52:53], s[46:47] offset:3072
	v_mul_f32_e32 v44, v28, v32
	v_mul_f32_e32 v45, v29, v32
	v_mul_f32_e32 v46, v30, v32
	v_mul_f32_e32 v47, v31, v32
	v_mul_f32_e32 v44, v92, v44
	v_mul_f32_e32 v45, v93, v45
	v_mul_f32_e32 v46, v94, v46
	v_mul_f32_e32 v47, v95, v47
	v_cvt_pk_bf16_f32 v54, v44, v45
	v_cvt_pk_bf16_f32 v55, v46, v47
	global_store_dwordx2 v105, v[54:55], s[46:47] offset:3584
	s_branch .Lp0_done_pa

; __device__ __forceinline__ unsigned pk2(float lo, float hi) { unsigned r; asm("v_cvt_pk_bf16_f32 %0, %1, %2" : "=v"(r) : "v"(lo), "v"(hi)); return r; }
; __device__ __forceinline__ void phase_prep(const Params& p, float* tile) {
;     ...
;     for (int r = blockIdx.x * 8 + wid; r < TROWS; r += gridDim.x * 8) {
;         const float* src = row_src(p, r); bf16_t* dst = XN + (size_t)r * DM;
;         if (!src) {
; #pragma unroll
;             for (int i = 0; i < 4; ++i) *(u32x4*)(dst + (lane + 64 * i) * 8) = (u32x4){0u, 0u, 0u, 0u};
;         } else {
;             f32x4 v[8]; float ss = 0.f;
; #pragma unroll
;             for (int i = 0; i < 8; ++i) { v[i] = __builtin_nontemporal_load((const f32x4*)src + lane + 64 * i); ss += v[i][0] * v[i][0] + v[i][1] * v[i][1] + v[i][2] * v[i][2] + v[i][3] * v[i][3]; }
; #pragma unroll
;             for (int o = 32; o >= 1; o >>= 1) ss += __shfl_xor(ss, o);
;             const float rs = rsqrtf(ss * (1.0f / DM) + EPS);
; #pragma unroll
;             for (int i = 0; i < 8; ++i) { const f32x4 w = ((const f32x4*)p.norm_w)[lane + 64 * i];
;                 u32x2 o; o.x = pk2(v[i][0] * rs * w[0], v[i][1] * rs * w[1]); o.y = pk2(v[i][2] * rs * w[2], v[i][3] * rs * w[3]);
;                 *(u32x2*)(dst + (lane + 64 * i) * 4) = o; }
;         }
;     }
.Lp0_exit:
	s_waitcnt vmcnt(0)
	s_mov_b32 s24, 0x78787879
	s_movk_i32 s25, 0xf780
	s_movk_i32 s26, 0x6f
	s_movk_i32 s27, 0x7f
	s_movk_i32 s28, 0x1000
	s_mov_b32 s29, 0x800000
	s_movk_i32 s30, 0x25ff
	s_mov_b32 s4, 0
	s_lshl_b32 s14, s90, 3
	s_movk_i32 s15, 0x21ff
	v_readlane_b32 s36, v244, 12
	v_readlane_b32 s37, v244, 13
	v_readlane_b32 s38, v244, 14
	v_readlane_b32 s39, v244, 15
	v_readlane_b32 s40, v244, 16
	v_readlane_b32 s41, v244, 17
	v_readlane_b32 s42, v244, 18
	v_readlane_b32 s43, v244, 19
	v_readlane_b32 s44, v244, 20
	v_readlane_b32 s45, v244, 21
	v_readlane_b32 s46, v244, 22
	v_readlane_b32 s47, v244, 23
	v_readlane_b32 s48, v244, 24
	v_readlane_b32 s49, v244, 25
	v_readlane_b32 s50, v244, 26
	v_readlane_b32 s51, v244, 27
	v_readlane_b32 s36, v244, 12
	v_mov_b32_e32 v23, 0
	v_or_b32_e32 v1, 0x100, v36
	v_lshlrev_b32_e32 v22, 4, v36
	v_readlane_b32 s48, v244, 24
	v_readlane_b32 s49, v244, 25
	v_or_b32_e32 v3, 0x140, v36
	v_or_b32_e32 v5, 0x180, v36
	v_lshl_add_u64 v[24:25], s[48:49], 0, v[22:23]
	v_lshlrev_b32_e32 v22, 4, v1
	v_lshl_add_u64 v[26:27], s[48:49], 0, v[22:23]
	v_lshlrev_b32_e32 v22, 4, v3
	v_lshlrev_b32_e32 v0, 3, v36
	v_lshlrev_b32_e32 v2, 2, v36
	v_or_b32_e32 v7, 0x1c0, v36
	v_lshl_add_u64 v[28:29], s[48:49], 0, v[22:23]
	v_lshlrev_b32_e32 v22, 4, v5
	v_mbcnt_hi_u32_b32 v60, -1, v184
	v_or_b32_e32 v4, 0x100, v2
	v_or_b32_e32 v6, 0x200, v2
	v_or_b32_e32 v8, 0x300, v2
	v_lshlrev_b32_e32 v10, 2, v1
	v_lshlrev_b32_e32 v12, 2, v3
	v_lshlrev_b32_e32 v14, 2, v5
	v_lshlrev_b32_e32 v16, 2, v7
	v_lshl_add_u64 v[30:31], s[48:49], 0, v[22:23]
	v_lshlrev_b32_e32 v22, 4, v7
	v_lshlrev_b32_e32 v54, 1, v0
	v_and_b32_e32 v0, 64, v60
	v_lshl_add_u64 v[32:33], s[48:49], 0, v[22:23]
	s_lshl_b32 s14, s90, 3
	s_mov_b64 s[8:9], 0
	s_movk_i32 s15, 0x21ff
	s_mov_b32 s24, 0x78787879
	s_movk_i32 s25, 0xf780
	s_movk_i32 s26, 0x6f
	s_movk_i32 s27, 0x7f
	v_lshlrev_b32_e32 v34, 4, v36
	s_movk_i32 s28, 0x1000
	s_mov_b32 s4, 0
	v_mov_b32_e32 v59, 0x358637bd
	s_mov_b32 s29, 0x800000
	v_lshlrev_b32_e32 v38, 1, v2
	v_lshlrev_b32_e32 v40, 1, v4
	v_lshlrev_b32_e32 v42, 1, v6
	v_lshlrev_b32_e32 v44, 1, v8
	v_lshlrev_b32_e32 v46, 1, v10
	v_lshlrev_b32_e32 v48, 1, v12
	v_lshlrev_b32_e32 v50, 1, v14
	v_lshlrev_b32_e32 v52, 1, v16
	s_movk_i32 s30, 0x25ff
	v_add_u32_e32 v61, 64, v0
	v_xor_b32_e32 v62, 32, v60
	v_xor_b32_e32 v63, 16, v60
	v_readlane_b32 s37, v244, 13
	v_readlane_b32 s38, v244, 14
	v_readlane_b32 s39, v244, 15
	v_readlane_b32 s40, v244, 16
	v_readlane_b32 s41, v244, 17
	v_readlane_b32 s42, v244, 18
	v_readlane_b32 s43, v244, 19
	v_readlane_b32 s44, v244, 20
	v_readlane_b32 s45, v244, 21
	v_readlane_b32 s46, v244, 22
	v_readlane_b32 s47, v244, 23
	v_readlane_b32 s50, v244, 26
	v_readlane_b32 s51, v244, 27

; __device__ __forceinline__ int tid_opaque() { int t = threadIdx.x; asm volatile("" : "+v"(t)); return t; }
; __device__ __forceinline__ float* row_dst(const Params& p, int r) {
;     if (r < ROWS_P) { const int b = r / TP, t = r - b * TP;
;         if (t < 128) return nullptr;
;         return p.out + O_YP + ((size_t)b * 2048 + (t - 128)) * DM; }
;     return p.out + O_YS + (size_t)(r - ROWS_P) * DM;
; }
; __device__ __forceinline__ void phase_final(const Params& p, int rb, int re, int vbid, int vG) {
;     const int tid = tid_opaque(); const int wid = tid >> 6, lane = tid & 63;
;     const float* RSS = (const float*)(p.ws + W_RSS);
;     for (int r = rb + vbid * 8 + wid; r < re; r += vG * 8) {
;         float* dst = row_dst(p, r); if (!dst) continue;
;         float ss = lane < 32 ? RSS[(size_t)r * 32 + lane] : 0.f;
; #pragma unroll
;         for (int o = 32; o >= 1; o >>= 1) ss += __shfl_xor(ss, o);
;         const float rs = rsqrtf(ss * (1.0f / DM) + EPS);
; #pragma unroll
;         for (int i = 0; i < 8; ++i) { f32x4 v = ((f32x4*)dst)[lane + 64 * i]; const f32x4 w = ((const f32x4*)p.final_norm_w)[lane + 64 * i];
;             v[0] *= rs * w[0]; v[1] *= rs * w[1]; v[2] *= rs * w[2]; v[3] *= rs * w[3]; ((f32x4*)dst)[lane + 64 * i] = v; }
.LBB0_1013:
	v_readlane_b32 s0, v242, 15
	v_ashrrev_i32_e32 v34, 6, v192
	v_and_b32_e32 v35, 63, v192
	v_readlane_b32 s38, v244, 47
	v_readlane_b32 s39, v244, 48
	v_readlane_b32 s40, v244, 49
	v_readlane_b32 s41, v244, 50
	v_readlane_b32 s42, v244, 51
	v_readlane_b32 s43, v244, 52
	v_readfirstlane_b32 s36, v34
	v_lshlrev_b32_e32 v128, 4, v35
	v_lshlrev_b32_e32 v130, 2, v35
	v_mov_b32_e32 v131, 0x358637bd
	v_add_u32_e32 v129, 0x1000, v128
	s_mov_b32 s51, 0x800000
	s_nop 3
	s_add_u32 s36, s36, s0
	s_addk_i32 s36, 0x1400
	s_cmp_lt_u32 s36, 0x2600
	s_cbranch_scc0 .Lfn_exit
	global_load_dwordx4 v[64:67], v128, s[38:39] offset:0
	global_load_dwordx4 v[68:71], v128, s[38:39] offset:1024
	global_load_dwordx4 v[72:75], v128, s[38:39] offset:2048
	global_load_dwordx4 v[76:79], v128, s[38:39] offset:3072
	global_load_dwordx4 v[80:83], v129, s[38:39] offset:0
	global_load_dwordx4 v[84:87], v129, s[38:39] offset:1024
	global_load_dwordx4 v[88:91], v129, s[38:39] offset:2048
	global_load_dwordx4 v[92:95], v129, s[38:39] offset:3072
	s_mov_b32 s55, 0
	s_cmp_lt_u32 s36, 0x2600
	s_cbranch_scc0 .Lfn_inv_a0
	s_cmp_gt_u32 s36, 0x21ff
	s_cbranch_scc1 .Lfn_smp_a0
	s_mul_hi_u32 s52, s36, 0x78787879
	s_lshr_b32 s52, s52, 10
	s_mul_i32 s53, s52, 0x880
	s_sub_u32 s53, s36, s53
	s_cmp_lt_u32 s53, 0x80
	s_cbranch_scc1 .Lfn_inv_a0
	s_lshl_b32 s52, s52, 24
	s_sub_u32 s53, s53, 0x80
	s_lshl_b32 s53, s53, 13
	s_add_u32 s52, s52, s53
	s_add_u32 s48, s40, s52
	s_addc_u32 s49, s41, 0
	s_branch .Lfn_done_a0
.Lfn_smp_a0:
	s_sub_u32 s53, s36, 0x2200
	s_lshl_b32 s53, s53, 13
	s_add_u32 s53, s53, 0x4000000
	s_add_u32 s48, s40, s53
	s_addc_u32 s49, s41, 0
	s_branch .Lfn_done_a0
.Lfn_inv_a0:
	s_mov_b32 s55, 1
	s_mov_b32 s48, s38
	s_mov_b32 s49, s39
.Lfn_done_a0:
	s_min_u32 s54, s36, 0x25ff
	s_lshl_b32 s54, s54, 7
	s_add_u32 s54, s54, 0x1bf20000
	s_add_u32 s46, s42, s54
	s_addc_u32 s47, s43, 0
	v_mov_b32_e32 v32, 0
	s_mov_b32 exec_hi, 0
	global_load_dword v32, v130, s[46:47]
	s_mov_b32 exec_hi, -1
	global_load_dwordx4 v[0:3], v128, s[48:49] offset:0
	global_load_dwordx4 v[4:7], v128, s[48:49] offset:1024
	global_load_dwordx4 v[8:11], v128, s[48:49] offset:2048
	global_load_dwordx4 v[12:15], v128, s[48:49] offset:3072
	global_load_dwordx4 v[16:19], v129, s[48:49] offset:0
	global_load_dwordx4 v[20:23], v129, s[48:49] offset:1024
	global_load_dwordx4 v[24:27], v129, s[48:49] offset:2048
	global_load_dwordx4 v[28:31], v129, s[48:49] offset:3072
	s_add_u32 s37, s36, 0x800
	s_mov_b32 s58, 0
	s_cmp_lt_u32 s37, 0x2600
	s_cbranch_scc0 .Lfn_inv_b0
	s_cmp_gt_u32 s37, 0x21ff
	s_cbranch_scc1 .Lfn_smp_b0
	s_mul_hi_u32 s52, s37, 0x78787879
	s_lshr_b32 s52, s52, 10
	s_mul_i32 s53, s52, 0x880
	s_sub_u32 s53, s37, s53
	s_cmp_lt_u32 s53, 0x80
	s_cbranch_scc1 .Lfn_inv_b0
	s_lshl_b32 s52, s52, 24
	s_sub_u32 s53, s53, 0x80
	s_lshl_b32 s53, s53, 13
	s_add_u32 s52, s52, s53
	s_add_u32 s56, s40, s52
	s_addc_u32 s57, s41, 0
	s_branch .Lfn_done_b0
.Lfn_smp_b0:
	s_sub_u32 s53, s37, 0x2200
	s_lshl_b32 s53, s53, 13
	s_add_u32 s53, s53, 0x4000000
	s_add_u32 s56, s40, s53
	s_addc_u32 s57, s41, 0
	s_branch .Lfn_done_b0
.Lfn_inv_b0:
	s_mov_b32 s58, 1
	s_mov_b32 s56, s38
	s_mov_b32 s57, s39
; __device__ __forceinline__ void phase_final(const Params& p, int rb, int re, int vbid, int vG) {
;     ...
;     for (int r = rb + vbid * 8 + wid; r < re; r += vG * 8) {
;         float* dst = row_dst(p, r); if (!dst) continue;
;         float ss = lane < 32 ? RSS[(size_t)r * 32 + lane] : 0.f;
; #pragma unroll
;         for (int o = 32; o >= 1; o >>= 1) ss += __shfl_xor(ss, o);
;         const float rs = rsqrtf(ss * (1.0f / DM) + EPS);
; #pragma unroll
;         for (int i = 0; i < 8; ++i) { f32x4 v = ((f32x4*)dst)[lane + 64 * i]; const f32x4 w = ((const f32x4*)p.final_norm_w)[lane + 64 * i];
;             v[0] *= rs * w[0]; v[1] *= rs * w[1]; v[2] *= rs * w[2]; v[3] *= rs * w[3]; ((f32x4*)dst)[lane + 64 * i] = v; }
.Lfn_done_b0:
	s_min_u32 s54, s37, 0x25ff
	s_lshl_b32 s54, s54, 7
	s_add_u32 s54, s54, 0x1bf20000
	s_add_u32 s46, s42, s54
	s_addc_u32 s47, s43, 0
	v_mov_b32_e32 v33, 0
	s_mov_b32 exec_hi, 0
	global_load_dword v33, v130, s[46:47]
	s_mov_b32 exec_hi, -1
	global_load_dwordx4 v[96:99], v128, s[56:57] offset:0
	global_load_dwordx4 v[100:103], v128, s[56:57] offset:1024
	global_load_dwordx4 v[104:107], v128, s[56:57] offset:2048
	global_load_dwordx4 v[108:111], v128, s[56:57] offset:3072
	global_load_dwordx4 v[112:115], v129, s[56:57] offset:0
	global_load_dwordx4 v[116:119], v129, s[56:57] offset:1024
	global_load_dwordx4 v[120:123], v129, s[56:57] offset:2048
	global_load_dwordx4 v[124:127], v129, s[56:57] offset:3072
	s_cmp_lg_u32 s55, 0
	s_cbranch_scc1 .Lfn_pdone_pa0
	s_waitcnt vmcnt(9)
	v_mov_b32_e32 v34, v32
	v_xor_b32_e32 v35, 0x80, v130
	ds_bpermute_b32 v36, v35, v34
	s_waitcnt lgkmcnt(0)
	v_add_f32_e32 v34, v34, v36
	v_xor_b32_e32 v35, 0x40, v130
	ds_bpermute_b32 v36, v35, v34
	s_waitcnt lgkmcnt(0)
	v_add_f32_e32 v34, v34, v36
	v_xor_b32_e32 v35, 0x20, v130
	ds_bpermute_b32 v36, v35, v34
	s_waitcnt lgkmcnt(0)
	v_add_f32_e32 v34, v34, v36
	v_xor_b32_e32 v35, 0x10, v130
	ds_bpermute_b32 v36, v35, v34
	s_waitcnt lgkmcnt(0)
	v_add_f32_e32 v34, v34, v36
	v_xor_b32_e32 v35, 0x8, v130
	ds_bpermute_b32 v36, v35, v34
	s_waitcnt lgkmcnt(0)
	v_add_f32_e32 v34, v34, v36
	v_xor_b32_e32 v35, 0x4, v130
	ds_bpermute_b32 v36, v35, v34
	s_waitcnt lgkmcnt(0)
	v_add_f32_e32 v34, v34, v36
	v_fmamk_f32 v34, v34, 0x3a000000, v131
	v_mul_f32_e32 v35, 0x4b800000, v34
	v_cmp_gt_f32_e32 vcc, s51, v34
	s_nop 1
	v_cndmask_b32_e32 v34, v34, v35, vcc
	v_rsq_f32_e32 v34, v34
	s_nop 0
	v_mul_f32_e32 v35, 0x45800000, v34
	v_cndmask_b32_e32 v34, v34, v35, vcc
	v_mul_f32_e32 v40, v64, v34
	v_mul_f32_e32 v41, v65, v34
	v_mul_f32_e32 v42, v66, v34
	v_mul_f32_e32 v43, v67, v34
	v_mul_f32_e32 v40, v0, v40
	v_mul_f32_e32 v41, v1, v41
	v_mul_f32_e32 v42, v2, v42
	v_mul_f32_e32 v43, v3, v43
	global_store_dwordx4 v128, v[40:43], s[48:49] offset:0
	v_mul_f32_e32 v44, v68, v34
	v_mul_f32_e32 v45, v69, v34
	v_mul_f32_e32 v46, v70, v34
	v_mul_f32_e32 v47, v71, v34
	v_mul_f32_e32 v44, v4, v44
	v_mul_f32_e32 v45, v5, v45
	v_mul_f32_e32 v46, v6, v46
	v_mul_f32_e32 v47, v7, v47
	global_store_dwordx4 v128, v[44:47], s[48:49] offset:1024
	v_mul_f32_e32 v48, v72, v34
	v_mul_f32_e32 v49, v73, v34
	v_mul_f32_e32 v50, v74, v34
	v_mul_f32_e32 v51, v75, v34
	v_mul_f32_e32 v48, v8, v48
	v_mul_f32_e32 v49, v9, v49
	v_mul_f32_e32 v50, v10, v50
	v_mul_f32_e32 v51, v11, v51
	global_store_dwordx4 v128, v[48:51], s[48:49] offset:2048
	v_mul_f32_e32 v52, v76, v34
	v_mul_f32_e32 v53, v77, v34
	v_mul_f32_e32 v54, v78, v34
	v_mul_f32_e32 v55, v79, v34
	v_mul_f32_e32 v52, v12, v52
	v_mul_f32_e32 v53, v13, v53
	v_mul_f32_e32 v54, v14, v54
	v_mul_f32_e32 v55, v15, v55
	global_store_dwordx4 v128, v[52:55], s[48:49] offset:3072
	v_mul_f32_e32 v40, v80, v34
	v_mul_f32_e32 v41, v81, v34
	v_mul_f32_e32 v42, v82, v34
	v_mul_f32_e32 v43, v83, v34
	v_mul_f32_e32 v40, v16, v40
	v_mul_f32_e32 v41, v17, v41
	v_mul_f32_e32 v42, v18, v42
	v_mul_f32_e32 v43, v19, v43
	global_store_dwordx4 v129, v[40:43], s[48:49] offset:0
	v_mul_f32_e32 v44, v84, v34
	v_mul_f32_e32 v45, v85, v34
	v_mul_f32_e32 v46, v86, v34
	v_mul_f32_e32 v47, v87, v34
	v_mul_f32_e32 v44, v20, v44
	v_mul_f32_e32 v45, v21, v45
	v_mul_f32_e32 v46, v22, v46
	v_mul_f32_e32 v47, v23, v47
	global_store_dwordx4 v129, v[44:47], s[48:49] offset:1024
	v_mul_f32_e32 v48, v88, v34
	v_mul_f32_e32 v49, v89, v34
	v_mul_f32_e32 v50, v90, v34
	v_mul_f32_e32 v51, v91, v34
	v_mul_f32_e32 v48, v24, v48
	v_mul_f32_e32 v49, v25, v49
	v_mul_f32_e32 v50, v26, v50
	v_mul_f32_e32 v51, v27, v51
	global_store_dwordx4 v129, v[48:51], s[48:49] offset:2048
	v_mul_f32_e32 v52, v92, v34
	v_mul_f32_e32 v53, v93, v34
	v_mul_f32_e32 v54, v94, v34
	v_mul_f32_e32 v55, v95, v34
	v_mul_f32_e32 v52, v28, v52
	v_mul_f32_e32 v53, v29, v53
	v_mul_f32_e32 v54, v30, v54
	v_mul_f32_e32 v55, v31, v55
	global_store_dwordx4 v129, v[52:55], s[48:49] offset:3072
.Lfn_pdone_pa0:
.Lfn_loop:
	s_cmp_lt_u32 s37, 0x2600
	s_cbranch_scc0 .Lfn_exit
	s_mov_b32 s59, s55
	s_add_u32 s36, s37, 0x800
	s_mov_b32 s55, 0
	s_cmp_lt_u32 s36, 0x2600
	s_cbranch_scc0 .Lfn_inv_a1
	s_cmp_gt_u32 s36, 0x21ff
	s_cbranch_scc1 .Lfn_smp_a1
	s_mul_hi_u32 s52, s36, 0x78787879
	s_lshr_b32 s52, s52, 10
	s_mul_i32 s53, s52, 0x880
	s_sub_u32 s53, s36, s53
	s_cmp_lt_u32 s53, 0x80
	s_cbranch_scc1 .Lfn_inv_a1
	s_lshl_b32 s52, s52, 24
	s_sub_u32 s53, s53, 0x80
	s_lshl_b32 s53, s53, 13
	s_add_u32 s52, s52, s53
	s_add_u32 s48, s40, s52
	s_addc_u32 s49, s41, 0
	s_branch .Lfn_done_a1

; __device__ __forceinline__ void phase_final(const Params& p, int rb, int re, int vbid, int vG) {
;     ...
;     for (int r = rb + vbid * 8 + wid; r < re; r += vG * 8) {
;         float* dst = row_dst(p, r); if (!dst) continue;
;         float ss = lane < 32 ? RSS[(size_t)r * 32 + lane] : 0.f;
.Lfn_done_a1:
	s_min_u32 s54, s36, 0x25ff
	s_lshl_b32 s54, s54, 7
	s_add_u32 s54, s54, 0x1bf20000
	s_add_u32 s46, s42, s54
	s_addc_u32 s47, s43, 0
	v_mov_b32_e32 v32, 0
	s_mov_b32 exec_hi, 0
	global_load_dword v32, v130, s[46:47]
	s_mov_b32 exec_hi, -1
	global_load_dwordx4 v[0:3], v128, s[48:49] offset:0
	global_load_dwordx4 v[4:7], v128, s[48:49] offset:1024
	global_load_dwordx4 v[8:11], v128, s[48:49] offset:2048
	global_load_dwordx4 v[12:15], v128, s[48:49] offset:3072
	global_load_dwordx4 v[16:19], v129, s[48:49] offset:0
	global_load_dwordx4 v[20:23], v129, s[48:49] offset:1024
	global_load_dwordx4 v[24:27], v129, s[48:49] offset:2048
	global_load_dwordx4 v[28:31], v129, s[48:49] offset:3072
	s_cmp_lg_u32 s58, 0
	s_cbranch_scc1 .Lfn_pdone_pb
	s_cmp_lg_u32 s59, 0
	s_cbranch_scc1 .Lfn_w9_pb
	s_waitcnt vmcnt(17)
	s_branch .Lfn_go_pb

; __device__ __forceinline__ void phase_final(const Params& p, int rb, int re, int vbid, int vG) {
;     ...
;     for (int r = rb + vbid * 8 + wid; r < re; r += vG * 8) {
;         float* dst = row_dst(p, r); if (!dst) continue;
;         float ss = lane < 32 ? RSS[(size_t)r * 32 + lane] : 0.f;
; #pragma unroll
;         for (int o = 32; o >= 1; o >>= 1) ss += __shfl_xor(ss, o);
;         const float rs = rsqrtf(ss * (1.0f / DM) + EPS);
; #pragma unroll
;         for (int i = 0; i < 8; ++i) { f32x4 v = ((f32x4*)dst)[lane + 64 * i]; const f32x4 w = ((const f32x4*)p.final_norm_w)[lane + 64 * i];
;             v[0] *= rs * w[0]; v[1] *= rs * w[1]; v[2] *= rs * w[2]; v[3] *= rs * w[3]; ((f32x4*)dst)[lane + 64 * i] = v; }
.Lfn_go_pb:
	v_mov_b32_e32 v34, v33
	v_xor_b32_e32 v35, 0x80, v130
	ds_bpermute_b32 v36, v35, v34
	s_waitcnt lgkmcnt(0)
	v_add_f32_e32 v34, v34, v36
	v_xor_b32_e32 v35, 0x40, v130
	ds_bpermute_b32 v36, v35, v34
	s_waitcnt lgkmcnt(0)
	v_add_f32_e32 v34, v34, v36
	v_xor_b32_e32 v35, 0x20, v130
	ds_bpermute_b32 v36, v35, v34
	s_waitcnt lgkmcnt(0)
	v_add_f32_e32 v34, v34, v36
	v_xor_b32_e32 v35, 0x10, v130
	ds_bpermute_b32 v36, v35, v34
	s_waitcnt lgkmcnt(0)
	v_add_f32_e32 v34, v34, v36
	v_xor_b32_e32 v35, 0x8, v130
	ds_bpermute_b32 v36, v35, v34
	s_waitcnt lgkmcnt(0)
	v_add_f32_e32 v34, v34, v36
	v_xor_b32_e32 v35, 0x4, v130
	ds_bpermute_b32 v36, v35, v34
	s_waitcnt lgkmcnt(0)
	v_add_f32_e32 v34, v34, v36
	v_fmamk_f32 v34, v34, 0x3a000000, v131
	v_mul_f32_e32 v35, 0x4b800000, v34
	v_cmp_gt_f32_e32 vcc, s51, v34
	s_nop 1
	v_cndmask_b32_e32 v34, v34, v35, vcc
	v_rsq_f32_e32 v34, v34
	s_nop 0
	v_mul_f32_e32 v35, 0x45800000, v34
	v_cndmask_b32_e32 v34, v34, v35, vcc
	v_mul_f32_e32 v40, v64, v34
	v_mul_f32_e32 v41, v65, v34
	v_mul_f32_e32 v42, v66, v34
	v_mul_f32_e32 v43, v67, v34
	v_mul_f32_e32 v40, v96, v40
	v_mul_f32_e32 v41, v97, v41
	v_mul_f32_e32 v42, v98, v42
	v_mul_f32_e32 v43, v99, v43
	global_store_dwordx4 v128, v[40:43], s[56:57] offset:0
	v_mul_f32_e32 v44, v68, v34
	v_mul_f32_e32 v45, v69, v34
	v_mul_f32_e32 v46, v70, v34
	v_mul_f32_e32 v47, v71, v34
	v_mul_f32_e32 v44, v100, v44
	v_mul_f32_e32 v45, v101, v45
	v_mul_f32_e32 v46, v102, v46
	v_mul_f32_e32 v47, v103, v47
	global_store_dwordx4 v128, v[44:47], s[56:57] offset:1024
	v_mul_f32_e32 v48, v72, v34
	v_mul_f32_e32 v49, v73, v34
	v_mul_f32_e32 v50, v74, v34
	v_mul_f32_e32 v51, v75, v34
	v_mul_f32_e32 v48, v104, v48
	v_mul_f32_e32 v49, v105, v49
	v_mul_f32_e32 v50, v106, v50
	v_mul_f32_e32 v51, v107, v51
	global_store_dwordx4 v128, v[48:51], s[56:57] offset:2048
	v_mul_f32_e32 v52, v76, v34
	v_mul_f32_e32 v53, v77, v34
	v_mul_f32_e32 v54, v78, v34
	v_mul_f32_e32 v55, v79, v34
	v_mul_f32_e32 v52, v108, v52
	v_mul_f32_e32 v53, v109, v53
	v_mul_f32_e32 v54, v110, v54
	v_mul_f32_e32 v55, v111, v55
	global_store_dwordx4 v128, v[52:55], s[56:57] offset:3072
	v_mul_f32_e32 v40, v80, v34
	v_mul_f32_e32 v41, v81, v34
	v_mul_f32_e32 v42, v82, v34
	v_mul_f32_e32 v43, v83, v34
	v_mul_f32_e32 v40, v112, v40
	v_mul_f32_e32 v41, v113, v41
	v_mul_f32_e32 v42, v114, v42
	v_mul_f32_e32 v43, v115, v43
	global_store_dwordx4 v129, v[40:43], s[56:57] offset:0
	v_mul_f32_e32 v44, v84, v34
	v_mul_f32_e32 v45, v85, v34
	v_mul_f32_e32 v46, v86, v34
	v_mul_f32_e32 v47, v87, v34
	v_mul_f32_e32 v44, v116, v44
	v_mul_f32_e32 v45, v117, v45
	v_mul_f32_e32 v46, v118, v46
	v_mul_f32_e32 v47, v119, v47
	global_store_dwordx4 v129, v[44:47], s[56:57] offset:1024
	v_mul_f32_e32 v48, v88, v34
	v_mul_f32_e32 v49, v89, v34
	v_mul_f32_e32 v50, v90, v34
	v_mul_f32_e32 v51, v91, v34
	v_mul_f32_e32 v48, v120, v48
	v_mul_f32_e32 v49, v121, v49
	v_mul_f32_e32 v50, v122, v50
	v_mul_f32_e32 v51, v123, v51
	global_store_dwordx4 v129, v[48:51], s[56:57] offset:2048
	v_mul_f32_e32 v52, v92, v34
	v_mul_f32_e32 v53, v93, v34
	v_mul_f32_e32 v54, v94, v34
	v_mul_f32_e32 v55, v95, v34
	v_mul_f32_e32 v52, v124, v52
	v_mul_f32_e32 v53, v125, v53
	v_mul_f32_e32 v54, v126, v54
	v_mul_f32_e32 v55, v127, v55
	global_store_dwordx4 v129, v[52:55], s[56:57] offset:3072
.Lfn_pdone_pb:
	s_cmp_lt_u32 s36, 0x2600
	s_cbranch_scc0 .Lfn_exit
	s_mov_b32 s59, s58
	s_add_u32 s37, s36, 0x800
	s_mov_b32 s58, 0
	s_cmp_lt_u32 s37, 0x2600
	s_cbranch_scc0 .Lfn_inv_b1
	s_cmp_gt_u32 s37, 0x21ff
	s_cbranch_scc1 .Lfn_smp_b1
	s_mul_hi_u32 s52, s37, 0x78787879
	s_lshr_b32 s52, s52, 10
	s_mul_i32 s53, s52, 0x880
	s_sub_u32 s53, s37, s53
	s_cmp_lt_u32 s53, 0x80
	s_cbranch_scc1 .Lfn_inv_b1
	s_lshl_b32 s52, s52, 24
	s_sub_u32 s53, s53, 0x80
	s_lshl_b32 s53, s53, 13
	s_add_u32 s52, s52, s53
	s_add_u32 s56, s40, s52
	s_addc_u32 s57, s41, 0
	s_branch .Lfn_done_b1

; __device__ __forceinline__ void phase_final(const Params& p, int rb, int re, int vbid, int vG) {
;     ...
;     for (int r = rb + vbid * 8 + wid; r < re; r += vG * 8) {
;         float* dst = row_dst(p, r); if (!dst) continue;
;         float ss = lane < 32 ? RSS[(size_t)r * 32 + lane] : 0.f;
.Lfn_done_b1:
	s_min_u32 s54, s37, 0x25ff
	s_lshl_b32 s54, s54, 7
	s_add_u32 s54, s54, 0x1bf20000
	s_add_u32 s46, s42, s54
	s_addc_u32 s47, s43, 0
	v_mov_b32_e32 v33, 0
	s_mov_b32 exec_hi, 0
	global_load_dword v33, v130, s[46:47]
	s_mov_b32 exec_hi, -1
	global_load_dwordx4 v[96:99], v128, s[56:57] offset:0
	global_load_dwordx4 v[100:103], v128, s[56:57] offset:1024
	global_load_dwordx4 v[104:107], v128, s[56:57] offset:2048
	global_load_dwordx4 v[108:111], v128, s[56:57] offset:3072
	global_load_dwordx4 v[112:115], v129, s[56:57] offset:0
	global_load_dwordx4 v[116:119], v129, s[56:57] offset:1024
	global_load_dwordx4 v[120:123], v129, s[56:57] offset:2048
	global_load_dwordx4 v[124:127], v129, s[56:57] offset:3072
	s_cmp_lg_u32 s55, 0
	s_cbranch_scc1 .Lfn_pdone_pa
	s_cmp_lg_u32 s59, 0
	s_cbranch_scc1 .Lfn_w9_pa
	s_waitcnt vmcnt(17)
	s_branch .Lfn_go_pa

; __device__ __forceinline__ void phase_final(const Params& p, int rb, int re, int vbid, int vG) {
;     ...
; #pragma unroll
;         for (int o = 32; o >= 1; o >>= 1) ss += __shfl_xor(ss, o);
;         const float rs = rsqrtf(ss * (1.0f / DM) + EPS);
; #pragma unroll
;         for (int i = 0; i < 8; ++i) { f32x4 v = ((f32x4*)dst)[lane + 64 * i]; const f32x4 w = ((const f32x4*)p.final_norm_w)[lane + 64 * i];
;             v[0] *= rs * w[0]; v[1] *= rs * w[1]; v[2] *= rs * w[2]; v[3] *= rs * w[3]; ((f32x4*)dst)[lane + 64 * i] = v; }
.Lfn_go_pa:
	v_mov_b32_e32 v34, v32
	v_xor_b32_e32 v35, 0x80, v130
	ds_bpermute_b32 v36, v35, v34
	s_waitcnt lgkmcnt(0)
	v_add_f32_e32 v34, v34, v36
	v_xor_b32_e32 v35, 0x40, v130
	ds_bpermute_b32 v36, v35, v34
	s_waitcnt lgkmcnt(0)
	v_add_f32_e32 v34, v34, v36
	v_xor_b32_e32 v35, 0x20, v130
	ds_bpermute_b32 v36, v35, v34
	s_waitcnt lgkmcnt(0)
	v_add_f32_e32 v34, v34, v36
	v_xor_b32_e32 v35, 0x10, v130
	ds_bpermute_b32 v36, v35, v34
	s_waitcnt lgkmcnt(0)
	v_add_f32_e32 v34, v34, v36
	v_xor_b32_e32 v35, 0x8, v130
	ds_bpermute_b32 v36, v35, v34
	s_waitcnt lgkmcnt(0)
	v_add_f32_e32 v34, v34, v36
	v_xor_b32_e32 v35, 0x4, v130
	ds_bpermute_b32 v36, v35, v34
	s_waitcnt lgkmcnt(0)
	v_add_f32_e32 v34, v34, v36
	v_fmamk_f32 v34, v34, 0x3a000000, v131
	v_mul_f32_e32 v35, 0x4b800000, v34
	v_cmp_gt_f32_e32 vcc, s51, v34
	s_nop 1
	v_cndmask_b32_e32 v34, v34, v35, vcc
	v_rsq_f32_e32 v34, v34
	s_nop 0
	v_mul_f32_e32 v35, 0x45800000, v34
	v_cndmask_b32_e32 v34, v34, v35, vcc
	v_mul_f32_e32 v40, v64, v34
	v_mul_f32_e32 v41, v65, v34
	v_mul_f32_e32 v42, v66, v34
	v_mul_f32_e32 v43, v67, v34
	v_mul_f32_e32 v40, v0, v40
	v_mul_f32_e32 v41, v1, v41
	v_mul_f32_e32 v42, v2, v42
	v_mul_f32_e32 v43, v3, v43
	global_store_dwordx4 v128, v[40:43], s[48:49] offset:0
	v_mul_f32_e32 v44, v68, v34
	v_mul_f32_e32 v45, v69, v34
	v_mul_f32_e32 v46, v70, v34
	v_mul_f32_e32 v47, v71, v34
	v_mul_f32_e32 v44, v4, v44
	v_mul_f32_e32 v45, v5, v45
	v_mul_f32_e32 v46, v6, v46
	v_mul_f32_e32 v47, v7, v47
	global_store_dwordx4 v128, v[44:47], s[48:49] offset:1024
	v_mul_f32_e32 v48, v72, v34
	v_mul_f32_e32 v49, v73, v34
	v_mul_f32_e32 v50, v74, v34
	v_mul_f32_e32 v51, v75, v34
	v_mul_f32_e32 v48, v8, v48
	v_mul_f32_e32 v49, v9, v49
	v_mul_f32_e32 v50, v10, v50
	v_mul_f32_e32 v51, v11, v51
	global_store_dwordx4 v128, v[48:51], s[48:49] offset:2048
	v_mul_f32_e32 v52, v76, v34
	v_mul_f32_e32 v53, v77, v34
	v_mul_f32_e32 v54, v78, v34
	v_mul_f32_e32 v55, v79, v34
	v_mul_f32_e32 v52, v12, v52
	v_mul_f32_e32 v53, v13, v53
	v_mul_f32_e32 v54, v14, v54
	v_mul_f32_e32 v55, v15, v55
	global_store_dwordx4 v128, v[52:55], s[48:49] offset:3072
	v_mul_f32_e32 v40, v80, v34
	v_mul_f32_e32 v41, v81, v34
	v_mul_f32_e32 v42, v82, v34
	v_mul_f32_e32 v43, v83, v34
	v_mul_f32_e32 v40, v16, v40
	v_mul_f32_e32 v41, v17, v41
	v_mul_f32_e32 v42, v18, v42
	v_mul_f32_e32 v43, v19, v43
	global_store_dwordx4 v129, v[40:43], s[48:49] offset:0
	v_mul_f32_e32 v44, v84, v34
	v_mul_f32_e32 v45, v85, v34
	v_mul_f32_e32 v46, v86, v34
	v_mul_f32_e32 v47, v87, v34
	v_mul_f32_e32 v44, v20, v44
	v_mul_f32_e32 v45, v21, v45
	v_mul_f32_e32 v46, v22, v46
	v_mul_f32_e32 v47, v23, v47
	global_store_dwordx4 v129, v[44:47], s[48:49] offset:1024
	v_mul_f32_e32 v48, v88, v34
	v_mul_f32_e32 v49, v89, v34
	v_mul_f32_e32 v50, v90, v34
	v_mul_f32_e32 v51, v91, v34
	v_mul_f32_e32 v48, v24, v48
	v_mul_f32_e32 v49, v25, v49
	v_mul_f32_e32 v50, v26, v50
	v_mul_f32_e32 v51, v27, v51
	global_store_dwordx4 v129, v[48:51], s[48:49] offset:2048
	v_mul_f32_e32 v52, v92, v34
	v_mul_f32_e32 v53, v93, v34
	v_mul_f32_e32 v54, v94, v34
	v_mul_f32_e32 v55, v95, v34
	v_mul_f32_e32 v52, v28, v52
	v_mul_f32_e32 v53, v29, v53
	v_mul_f32_e32 v54, v30, v54
	v_mul_f32_e32 v55, v31, v55
	global_store_dwordx4 v129, v[52:55], s[48:49] offset:3072

; __global__ void __launch_bounds__(512, 2) fwd_megakernel(Params p) {
;     ...
;     phase_final(p, 5120, TROWS, blockIdx.x, gridDim.x);
; }
.Lfn_exit:
.LBB0_1024:
	s_endpgm
